# lever 4 variant: static s_setprio 1 for waves 0-3 (older half) instead of waves 4-7; K-loop flips deleted
# baseline (speedup 1.0000x reference)
; #define PG8_STAGE(bufoff, gbase, voff) do { _Pragma("unroll") for (int _i = 0; _i < 2; ++_i) \
;         __builtin_amdgcn_global_load_lds((const unsigned*)((const char*)(gbase) + (voff)[_i]), (PG8_LAS unsigned*)(lds + (bufoff) + ldsw + _i * 8192), 16, 0, 0); } while (0)
; #define PG8_WAIT_V(n) asm volatile("s_waitcnt vmcnt(" #n ")" ::: "memory")
; #define PG8_BAR __builtin_amdgcn_s_barrier()
; template <class Epi, class Sched, bool ALIGN_EPI = false, bool SP2 = false>
; __device__ __forceinline__ void gemm_phase(PG8_LAS unsigned char* lds, const Gemm g, const Sched& S, const Epi& E) {
;     ...
;     const int aoff = lds_byte(wr * 64 + fr, fq * 8), boff = lds_byte(wc * 32 + fr, fq * 8);
;     ...
;         PG8_WAIT_V(2); PG8_BAR;
;         PG8_STAGE(PG8_SB(1, 0), cB + kstep, voffB); PG8_STAGE(PG8_SA(1, 0), cA + kstep, voffA); PG8_STAGE(PG8_SB(1, 1), cB + hB + kstep, voffB);
;         PG8_WAIT_V(6); PG8_BAR;
.LBB0_184:
	s_add_u32 s14, s0, 0x15800000
	s_waitcnt vmcnt(0)
	v_bfe_u32 v19, v10, 4, 2
	s_addc_u32 s15, s1, 0
	v_and_b32_e32 v18, 15, v10
	v_lshlrev_b32_e32 v20, 3, v19
	v_lshlrev_b32_e32 v19, 4, v19
	s_add_u32 s16, s0, 0x1d800000
	v_lshl_or_b32 v1, s5, 6, v18
	v_lshl_or_b32 v19, v18, 6, v19
	v_lshlrev_b32_e32 v18, 2, v18
	s_mov_b64 s[38:39], 0x80
	s_addc_u32 s17, s1, 0
	s_and_b32 s8, s4, 3
	s_lshl_b32 s4, s5, 13
	v_and_b32_e32 v21, 32, v18
	s_add_i32 m0, s74, 0x18000
	v_lshl_add_u64 v[8:9], v[8:9], 0, s[38:39]
	v_bitop3_b32 v22, v19, s4, v21 bitop3:0xde
	s_lshl_b32 s4, s8, 12
	s_waitcnt vmcnt(2)
	s_barrier
	global_load_lds_dwordx4 v[8:9], off
	v_lshl_add_u64 v[6:7], v[6:7], 0, s[38:39]
	s_add_i32 m0, s74, 0x1a000
	s_add_i32 s81, s74, 0x8000
	s_add_i32 s82, s74, 0xa000
	v_bitop3_b32 v223, v19, s4, v21 bitop3:0xde
	global_load_lds_dwordx4 v[6:7], off
	v_lshl_add_u64 v[4:5], v[4:5], 0, s[38:39]
	s_mov_b32 m0, s81
	s_add_u32 s4, s64, 0x80080
	global_load_lds_dwordx4 v[4:5], off
	v_lshl_add_u64 v[2:3], v[2:3], 0, s[38:39]
	s_mov_b32 m0, s82
	s_addc_u32 s5, s65, 0
	global_load_lds_dwordx4 v[2:3], off
	s_add_i32 m0, s74, 0x1c000
	v_lshl_add_u64 v[2:3], s[4:5], 0, v[196:197]
	global_load_lds_dwordx4 v[2:3], off
	v_lshl_add_u64 v[2:3], s[4:5], 0, v[200:201]
	s_add_i32 m0, s74, 0x1e000
	v_lshrrev_b32_e32 v17, 4, v10
	global_load_lds_dwordx4 v[2:3], off
	v_and_b32_e32 v2, 3, v10
	s_cmpk_lt_u32 s6, 0x100
	v_lshlrev_b32_e32 v3, 1, v2
	v_cmp_gt_u32_e64 s[6:7], 2, v2
	v_bfe_u32 v2, v17, 1, 1
	v_lshl_or_b32 v227, s8, 2, v2
	v_lshlrev_b32_e32 v2, 1, v10
	v_or_b32_e32 v5, v20, v3
	v_and_b32_e32 v228, 32, v2
	v_bitop3_b32 v2, v20, 18, v3 bitop3:0xc8
	v_lshrrev_b32_e32 v3, 2, v10
	s_cselect_b64 s[40:41], -1, 0
	s_lshl_b32 s9, s8, 8
	v_and_b32_e32 v6, 4, v10
	v_and_b32_e32 v3, 4, v3
	v_or3_b32 v5, v21, s9, v5
	v_and_b32_e32 v7, 1, v10
	v_and_or_b32 v3, v18, 40, v3
	v_lshlrev_b32_e32 v6, 1, v6
	v_cmp_eq_u32_e64 s[4:5], 0, v7
	v_or3_b32 v7, v3, v2, s9
	v_lshl_or_b32 v202, v5, 4, v6
	v_lshl_or_b32 v4, s8, 5, v20
	v_lshl_add_u64 v[2:3], s[0:1], 0, v[202:203]
	s_mov_b64 s[8:9], 0xd800000
	v_lshl_or_b32 v202, v7, 4, v6
	v_lshl_add_u64 v[204:205], v[2:3], 0, s[8:9]
	v_lshl_add_u64 v[2:3], s[0:1], 0, v[202:203]
	s_mov_b64 s[8:9], 0x11800000
	v_lshlrev_b32_e32 v202, 2, v4
	v_lshl_add_u64 v[206:207], v[2:3], 0, s[8:9]
	v_lshl_add_u64 v[2:3], s[0:1], 0, v[202:203]
	s_mov_b64 s[42:43], 0x100000
	s_mov_b64 s[8:9], 0x300000
	v_lshl_add_u64 v[208:209], v[2:3], 0, s[42:43]
	v_lshl_add_u64 v[210:211], v[2:3], 0, s[8:9]
	v_lshlrev_b32_e32 v2, 15, v11
	v_and_b32_e32 v2, 0xffff0000, v2
	v_lshl_add_u32 v2, v12, 12, v2
	v_and_b32_e32 v3, 1, v11
	v_lshl_or_b32 v2, v3, 6, v2
	v_lshl_add_u32 v212, v13, 1, v2
	v_lshlrev_b32_e32 v2, 15, v14
	v_and_b32_e32 v2, 0xffff0000, v2
	s_waitcnt vmcnt(6)
	v_lshl_add_u32 v2, v15, 12, v2
	v_and_b32_e32 v3, 1, v14
	v_lshl_or_b32 v2, v3, 6, v2
	s_add_i32 s84, 0, 0x10000
	s_add_i32 s85, 0, 0x14000
	v_or_b32_e32 v224, 0xffffdc00, v4
	v_or_b32_e32 v225, 0xffffe000, v4
	v_or_b32_e32 v226, 0xffffe800, v4
	s_waitcnt lgkmcnt(0)
	s_ashr_i32 s83, s78, 31
	v_mov_b32_e32 v213, v203
	v_lshl_add_u32 v214, v16, 1, v2
	v_mov_b32_e32 v215, v203
	v_mov_b64_e32 v[216:217], 0xd00
	v_mov_b64_e32 v[218:219], 0xcff
	v_add_u32_e32 v229, s84, v223
	v_add_u32_e32 v230, s85, v223
	v_add_u32_e32 v231, 0, v22
	s_mov_b32 s18, 0x58000
	s_mov_b32 s87, 0x80000
	s_mov_b64 s[44:45], 0x90000
	s_mov_b32 s88, 0x90000
	s_mov_b64 s[46:47], 0xa0000
	s_mov_b32 s89, 0xa0000
	s_mov_b64 s[48:49], 0xb0000
	s_mov_b32 s90, 0xb0000
	s_mov_b32 s91, 0x5040100
	s_mov_b32 s92, 0x7060302
	s_mov_b32 s93, 0x9800000
	s_mov_b32 s94, 0xc2fc0000
	s_mov_b32 s95, 0x800000
	s_mov_b32 s50, 0x3d800000
	v_mov_b32_e32 v232, 0x42800000
	v_mov_b32_e32 v233, 0x42000000
	v_not_b32_e32 v234, 63
	s_barrier
	v_readfirstlane_b32 s99, v0
	s_nop 3
	s_lshr_b32 s99, s99, 8
	s_cmp_eq_u32 s99, 0
	s_cbranch_scc0 .Lprio_skip_1
	s_setprio 1

; #define PG8_STAGE(bufoff, gbase, voff) do { _Pragma("unroll") for (int _i = 0; _i < 2; ++_i) \
;         __builtin_amdgcn_global_load_lds((const unsigned*)((const char*)(gbase) + (voff)[_i]), (PG8_LAS unsigned*)(lds + (bufoff) + ldsw + _i * 8192), 16, 0, 0); } while (0)
; #define PG8_WAIT_V(n) asm volatile("s_waitcnt vmcnt(" #n ")" ::: "memory")
; #define PG8_BAR __builtin_amdgcn_s_barrier()
; template <class Epi, class Sched, bool ALIGN_EPI = false, bool SP2 = false>
; __device__ __forceinline__ void gemm_phase(PG8_LAS unsigned char* lds, const Gemm g, const Sched& S, const Epi& E) {
;     ...
;     const int aoff = lds_byte(wr * 64 + fr, fq * 8), boff = lds_byte(wc * 32 + fr, fq * 8);
;     ...
;         PG8_WAIT_V(2); PG8_BAR;
;         PG8_STAGE(PG8_SB(1, 0), cB + kstep, voffB); PG8_STAGE(PG8_SA(1, 0), cA + kstep, voffA); PG8_STAGE(PG8_SB(1, 1), cB + hB + kstep, voffB);
;         PG8_WAIT_V(6); PG8_BAR;
.LBB0_775:
	s_add_u32 s10, s6, 0x1d800000
	s_addc_u32 s11, s7, 0
	s_lshl_b32 s12, s12, 5
	s_and_b32 s18, s12, 0x60
	s_mov_b64 s[12:13], 0x80
	s_add_i32 m0, s39, 0x18000
	v_lshl_add_u64 v[8:9], v[8:9], 0, s[12:13]
	s_lshl_b32 s15, s14, 13
	s_lshl_b32 s19, s18, 7
	s_waitcnt vmcnt(2)
	s_barrier
	global_load_lds_dwordx4 v[8:9], off
	v_lshl_add_u64 v[6:7], v[6:7], 0, s[12:13]
	s_add_i32 m0, s39, 0x1a000
	s_add_i32 s77, s39, 0x8000
	s_add_i32 s78, s39, 0xa000
	global_load_lds_dwordx4 v[6:7], off
	v_lshl_add_u64 v[4:5], v[4:5], 0, s[12:13]
	s_mov_b32 m0, s77
	s_add_u32 s16, s42, 0x10080
	global_load_lds_dwordx4 v[4:5], off
	v_lshl_add_u64 v[2:3], v[2:3], 0, s[12:13]
	s_mov_b32 m0, s78
	s_addc_u32 s17, s43, 0
	global_load_lds_dwordx4 v[2:3], off
	s_add_i32 m0, s39, 0x1c000
	v_lshl_add_u64 v[2:3], s[16:17], 0, v[134:135]
	global_load_lds_dwordx4 v[2:3], off
	v_lshl_add_u64 v[2:3], s[16:17], 0, v[130:131]
	s_add_i32 m0, s39, 0x1e000
	s_cmpk_lt_u32 s5, 0x100
	global_load_lds_dwordx4 v[2:3], off
	v_lshrrev_b32_e32 v3, 1, v10
	v_and_b32_e32 v3, 24, v3
	v_and_b32_e32 v2, 15, v10
	v_lshlrev_b32_e32 v4, 1, v3
	v_lshl_or_b32 v142, s14, 6, v2
	v_lshl_or_b32 v2, v2, 6, v4
	v_lshlrev_b32_e32 v4, 2, v10
	v_and_b32_e32 v4, 32, v4
	s_waitcnt vmcnt(6)
	v_bitop3_b32 v5, v2, s15, v4 bitop3:0xde
	v_bitop3_b32 v143, v2, s19, v4 bitop3:0xde
	s_cselect_b64 s[14:15], -1, 0
	s_add_i32 s80, 0, 0x10000
	s_add_i32 s81, 0, 0x14000
	s_sext_i32_i8 s86, s4
	s_waitcnt lgkmcnt(0)
	s_ashr_i32 s79, s33, 31
	v_or_b32_e32 v144, s18, v3
	v_mov_b64_e32 v[138:139], 0x100
	v_mov_b64_e32 v[140:141], 0xff
	v_add_u32_e32 v145, s80, v143
	v_add_u32_e32 v146, s81, v143
	v_add_u32_e32 v147, 0, v5
	s_mov_b32 s82, 0x40000
	s_mov_b64 s[16:17], 0x48000
	s_mov_b32 s83, 0x48000
	s_mov_b64 s[20:21], 0x50000
	s_mov_b32 s84, 0x50000
	s_mov_b64 s[22:23], 0x58000
	s_mov_b32 s85, 0x58000
	s_barrier
	s_waitcnt vmcnt(0)
	v_readfirstlane_b32 s99, v0
	s_nop 3
	s_lshr_b32 s99, s99, 8
	s_cmp_eq_u32 s99, 0
	s_cbranch_scc0 .Lprio_skip_2
	s_setprio 1

; #define PG8_STAGE(bufoff, gbase, voff) do { _Pragma("unroll") for (int _i = 0; _i < 2; ++_i) \
;         __builtin_amdgcn_global_load_lds((const unsigned*)((const char*)(gbase) + (voff)[_i]), (PG8_LAS unsigned*)(lds + (bufoff) + ldsw + _i * 8192), 16, 0, 0); } while (0)
; #define PG8_WAIT_V(n) asm volatile("s_waitcnt vmcnt(" #n ")" ::: "memory")
; #define PG8_BAR __builtin_amdgcn_s_barrier()
; template <class Epi, class Sched, bool ALIGN_EPI = false, bool SP2 = false>
; __device__ __forceinline__ void gemm_phase(PG8_LAS unsigned char* lds, const Gemm g, const Sched& S, const Epi& E) {
;     ...
;     const int aoff = lds_byte(wr * 64 + fr, fq * 8), boff = lds_byte(wc * 32 + fr, fq * 8);
;     ...
;         PG8_WAIT_V(2); PG8_BAR;
;         PG8_STAGE(PG8_SB(1, 0), cB + kstep, voffB); PG8_STAGE(PG8_SA(1, 0), cA + kstep, voffA); PG8_STAGE(PG8_SB(1, 1), cB + hB + kstep, voffB);
;         PG8_WAIT_V(6); PG8_BAR;
.LBB0_858:
	s_add_u32 s6, s4, 0xd800000
	s_addc_u32 s7, s5, 0
	s_lshl_b32 s4, s8, 5
	s_mov_b64 s[8:9], 0x80
	s_and_b32 s18, s4, 0x60
	s_add_i32 m0, s41, 0x18000
	v_lshl_add_u64 v[8:9], v[8:9], 0, s[8:9]
	s_lshl_b32 s17, s16, 13
	s_lshl_b32 s19, s18, 7
	s_waitcnt vmcnt(2)
	s_barrier
	global_load_lds_dwordx4 v[8:9], off
	v_lshl_add_u64 v[6:7], v[6:7], 0, s[8:9]
	s_add_i32 m0, s41, 0x1a000
	s_add_i32 s60, s41, 0x8000
	s_add_i32 s61, s41, 0xa000
	global_load_lds_dwordx4 v[6:7], off
	v_lshl_add_u64 v[2:3], v[2:3], 0, s[8:9]
	s_mov_b32 m0, s60
	s_add_u32 s4, s44, 0x40080
	global_load_lds_dwordx4 v[2:3], off
	v_lshl_add_u64 v[2:3], v[4:5], 0, s[8:9]
	s_mov_b32 m0, s61
	s_addc_u32 s5, s45, 0
	global_load_lds_dwordx4 v[2:3], off
	s_add_i32 m0, s41, 0x1c000
	v_lshl_add_u64 v[2:3], s[4:5], 0, v[134:135]
	global_load_lds_dwordx4 v[2:3], off
	v_lshl_add_u64 v[2:3], s[4:5], 0, v[130:131]
	s_add_i32 m0, s41, 0x1e000
	s_cmpk_lt_u32 s15, 0x100
	global_load_lds_dwordx4 v[2:3], off
	v_lshrrev_b32_e32 v3, 1, v11
	v_and_b32_e32 v3, 24, v3
	v_and_b32_e32 v2, 15, v11
	v_lshlrev_b32_e32 v4, 1, v3
	v_lshl_or_b32 v1, s16, 6, v2
	v_lshl_or_b32 v2, v2, 6, v4
	v_lshlrev_b32_e32 v4, 2, v11
	v_and_b32_e32 v4, 32, v4
	v_bitop3_b32 v5, v2, s17, v4 bitop3:0xde
	v_bitop3_b32 v154, v2, s19, v4 bitop3:0xde
	v_lshlrev_b32_e32 v2, 14, v15
	v_and_b32_e32 v2, 0xffff8000, v2
	v_or_b32_e32 v155, s18, v3
	v_lshl_add_u32 v2, v14, 11, v2
	v_and_b32_e32 v3, 1, v15
	v_lshl_or_b32 v2, v3, 6, v2
	v_lshl_add_u32 v138, v16, 1, v2
	v_lshlrev_b32_e32 v2, 14, v10
	v_and_b32_e32 v2, 0xffff8000, v2
	s_waitcnt vmcnt(6)
	v_lshl_add_u32 v2, v12, 11, v2
	v_and_b32_e32 v3, 1, v10
	s_sext_i32_i8 s66, s14
	s_cselect_b64 s[14:15], -1, 0
	v_lshl_or_b32 v2, v3, 6, v2
	s_add_i32 s64, 0, 0x10000
	s_add_i32 s65, 0, 0x14000
	s_mov_b32 s62, 0
	s_waitcnt lgkmcnt(0)
	s_ashr_i32 s63, s50, 31
	v_mov_b32_e32 v139, v135
	v_lshl_add_u32 v140, v13, 1, v2
	v_mov_b32_e32 v141, v135
	v_mov_b64_e32 v[142:143], 0x200
	v_mov_b64_e32 v[144:145], 0x1ff
	v_add_u32_e32 v156, s64, v154
	v_add_u32_e32 v157, s65, v154
	v_add_u32_e32 v158, 0, v5
	s_mov_b64 s[16:17], 0x1000
	s_barrier
	v_readfirstlane_b32 s99, v0
	s_nop 3
	s_lshr_b32 s99, s99, 8
	s_cmp_eq_u32 s99, 0
	s_cbranch_scc0 .Lprio_skip_3
	s_setprio 1

; #define PG8_STAGE(bufoff, gbase, voff) do { _Pragma("unroll") for (int _i = 0; _i < 2; ++_i) \
;         __builtin_amdgcn_global_load_lds((const unsigned*)((const char*)(gbase) + (voff)[_i]), (PG8_LAS unsigned*)(lds + (bufoff) + ldsw + _i * 8192), 16, 0, 0); } while (0)
; #define PG8_WAIT_V(n) asm volatile("s_waitcnt vmcnt(" #n ")" ::: "memory")
; #define PG8_BAR __builtin_amdgcn_s_barrier()
; template <class Epi, class Sched, bool ALIGN_EPI = false, bool SP2 = false>
; __device__ __forceinline__ void gemm_phase(PG8_LAS unsigned char* lds, const Gemm g, const Sched& S, const Epi& E) {
;     ...
;     const int aoff = lds_byte(wr * 64 + fr, fq * 8), boff = lds_byte(wc * 32 + fr, fq * 8);
;     ...
;         PG8_WAIT_V(2); PG8_BAR;
;         PG8_STAGE(PG8_SB(1, 0), cB + kstep, voffB); PG8_STAGE(PG8_SA(1, 0), cA + kstep, voffA); PG8_STAGE(PG8_SB(1, 1), cB + hB + kstep, voffB);
;         PG8_WAIT_V(6); PG8_BAR;
.LBB0_878:
	s_add_u32 s8, s6, 0xd800000
	s_addc_u32 s9, s7, 0
	s_add_u32 s14, s6, 0x9800000
	s_addc_u32 s15, s7, 0
	s_lshl_b32 s6, s16, 5
	s_mov_b64 s[16:17], 0x80
	s_and_b32 s19, s6, 0x60
	s_add_i32 m0, s43, 0x18000
	v_lshl_add_u64 v[8:9], v[8:9], 0, s[16:17]
	s_lshl_b32 s18, s22, 13
	s_lshl_b32 s23, s19, 7
	s_waitcnt vmcnt(2)
	s_barrier
	global_load_lds_dwordx4 v[8:9], off
	v_lshl_add_u64 v[6:7], v[6:7], 0, s[16:17]
	s_add_i32 m0, s43, 0x1a000
	s_add_i32 s63, s43, 0x8000
	s_add_i32 s64, s43, 0xa000
	global_load_lds_dwordx4 v[6:7], off
	v_lshl_add_u64 v[2:3], v[2:3], 0, s[16:17]
	s_mov_b32 m0, s63
	s_add_u32 s6, s46, 0x80080
	global_load_lds_dwordx4 v[2:3], off
	v_lshl_add_u64 v[2:3], v[4:5], 0, s[16:17]
	s_mov_b32 m0, s64
	s_addc_u32 s7, s47, 0
	global_load_lds_dwordx4 v[2:3], off
	s_add_i32 m0, s43, 0x1c000
	v_lshl_add_u64 v[2:3], s[6:7], 0, v[150:151]
	global_load_lds_dwordx4 v[2:3], off
	v_lshl_add_u64 v[2:3], s[6:7], 0, v[146:147]
	s_add_i32 m0, s43, 0x1e000
	s_cmpk_lt_u32 s21, 0x100
	global_load_lds_dwordx4 v[2:3], off
	v_lshrrev_b32_e32 v3, 1, v11
	v_and_b32_e32 v3, 24, v3
	v_and_b32_e32 v2, 15, v11
	v_lshlrev_b32_e32 v4, 1, v3
	v_lshl_or_b32 v1, s22, 6, v2
	v_lshl_or_b32 v2, v2, 6, v4
	v_lshlrev_b32_e32 v4, 2, v11
	v_and_b32_e32 v4, 32, v4
	v_bitop3_b32 v5, v2, s18, v4 bitop3:0xde
	v_bitop3_b32 v170, v2, s23, v4 bitop3:0xde
	v_lshlrev_b32_e32 v2, 15, v15
	v_and_b32_e32 v2, 0xffff0000, v2
	v_or_b32_e32 v171, s19, v3
	v_lshl_add_u32 v2, v14, 12, v2
	v_and_b32_e32 v3, 1, v15
	v_lshl_or_b32 v2, v3, 6, v2
	v_lshl_add_u32 v154, v16, 1, v2
	v_lshlrev_b32_e32 v2, 15, v10
	v_and_b32_e32 v2, 0xffff0000, v2
	s_waitcnt vmcnt(6)
	v_lshl_add_u32 v2, v12, 12, v2
	v_and_b32_e32 v3, 1, v10
	s_sext_i32_i8 s69, s20
	s_cselect_b64 s[20:21], -1, 0
	v_lshl_or_b32 v2, v3, 6, v2
	s_add_i32 s66, 0, 0x10000
	s_add_i32 s67, 0, 0x14000
	s_waitcnt lgkmcnt(0)
	s_ashr_i32 s65, s50, 31
	v_mov_b32_e32 v155, v151
	v_lshl_add_u32 v156, v13, 1, v2
	v_mov_b32_e32 v157, v151
	v_mov_b64_e32 v[158:159], 0x200
	v_mov_b64_e32 v[160:161], 0x1ff
	v_add_u32_e32 v172, s66, v170
	v_add_u32_e32 v173, s67, v170
	v_add_u32_e32 v174, 0, v5
	s_barrier
	v_readfirstlane_b32 s99, v0
	s_nop 3
	s_lshr_b32 s99, s99, 8
	s_cmp_eq_u32 s99, 0
	s_cbranch_scc0 .Lprio_skip_4
	s_setprio 1

; #define PG8_STAGE(bufoff, gbase, voff) do { _Pragma("unroll") for (int _i = 0; _i < 2; ++_i) \
;         __builtin_amdgcn_global_load_lds((const unsigned*)((const char*)(gbase) + (voff)[_i]), (PG8_LAS unsigned*)(lds + (bufoff) + ldsw + _i * 8192), 16, 0, 0); } while (0)
; #define PG8_WAIT_V(n) asm volatile("s_waitcnt vmcnt(" #n ")" ::: "memory")
; #define PG8_BAR __builtin_amdgcn_s_barrier()
; template <class Epi, class Sched, bool ALIGN_EPI = false, bool SP2 = false>
; __device__ __forceinline__ void gemm_phase(PG8_LAS unsigned char* lds, const Gemm g, const Sched& S, const Epi& E) {
;     ...
;     const int aoff = lds_byte(wr * 64 + fr, fq * 8), boff = lds_byte(wc * 32 + fr, fq * 8);
;     ...
;         PG8_WAIT_V(2); PG8_BAR;
;         PG8_STAGE(PG8_SB(1, 0), cB + kstep, voffB); PG8_STAGE(PG8_SA(1, 0), cA + kstep, voffA); PG8_STAGE(PG8_SB(1, 1), cB + hB + kstep, voffB);
;         PG8_WAIT_V(6); PG8_BAR;
.LBB0_953:
	s_add_u32 s16, s6, 0x15800000
	s_addc_u32 s17, s7, 0
	s_add_u32 s20, s6, 0x1e00000
	s_mov_b64 s[22:23], 0x80
	s_addc_u32 s21, s7, 0
	s_and_b32 s67, s9, 3
	s_add_i32 m0, s62, 0x18000
	v_lshl_add_u64 v[8:9], v[8:9], 0, s[22:23]
	s_lshl_b32 s9, s24, 13
	s_lshl_b32 s18, s67, 12
	s_waitcnt vmcnt(2)
	s_barrier
	global_load_lds_dwordx4 v[8:9], off
	v_lshl_add_u64 v[6:7], v[6:7], 0, s[22:23]
	s_add_i32 m0, s62, 0x1a000
	s_add_i32 s69, s62, 0x8000
	s_add_i32 s70, s62, 0xa000
	global_load_lds_dwordx4 v[6:7], off
	v_lshl_add_u64 v[2:3], v[2:3], 0, s[22:23]
	s_mov_b32 m0, s69
	s_add_u32 s6, s50, 0x80080
	global_load_lds_dwordx4 v[2:3], off
	v_lshl_add_u64 v[2:3], v[4:5], 0, s[22:23]
	s_mov_b32 m0, s70
	s_addc_u32 s7, s51, 0
	global_load_lds_dwordx4 v[2:3], off
	s_add_i32 m0, s62, 0x1c000
	v_lshl_add_u64 v[2:3], s[6:7], 0, v[180:181]
	global_load_lds_dwordx4 v[2:3], off
	v_lshl_add_u64 v[2:3], s[6:7], 0, v[184:185]
	s_add_i32 m0, s62, 0x1e000
	s_cmpk_lt_u32 s8, 0x100
	global_load_lds_dwordx4 v[2:3], off
	v_bfe_u32 v3, v10, 4, 2
	v_and_b32_e32 v2, 15, v10
	v_lshlrev_b32_e32 v5, 4, v3
	v_lshl_or_b32 v1, s24, 6, v2
	v_lshl_or_b32 v2, v2, 6, v5
	v_lshlrev_b32_e32 v5, 2, v10
	v_and_b32_e32 v5, 32, v5
	v_bitop3_b32 v6, v2, s9, v5 bitop3:0xde
	v_bitop3_b32 v206, v2, s18, v5 bitop3:0xde
	v_lshlrev_b32_e32 v2, 15, v11
	v_and_b32_e32 v2, 0xffff0000, v2
	v_lshlrev_b32_e32 v4, 3, v3
	v_cmp_eq_u32_e64 s[6:7], 0, v3
	v_lshl_add_u32 v2, v12, 12, v2
	v_and_b32_e32 v3, 1, v11
	v_lshl_or_b32 v2, v3, 6, v2
	v_lshl_add_u32 v186, v13, 1, v2
	v_lshlrev_b32_e32 v2, 15, v14
	v_and_b32_e32 v2, 0xffff0000, v2
	s_waitcnt vmcnt(6)
	v_lshl_add_u32 v2, v15, 12, v2
	v_and_b32_e32 v3, 1, v14
	s_cselect_b64 s[24:25], -1, 0
	v_lshl_or_b32 v2, v3, 6, v2
	s_add_i32 s72, 0, 0x10000
	s_add_i32 s73, 0, 0x14000
	v_lshl_or_b32 v207, s67, 5, v4
	s_waitcnt lgkmcnt(0)
	s_ashr_i32 s71, s66, 31
	v_mov_b32_e32 v187, v181
	v_lshl_add_u32 v188, v16, 1, v2
	v_mov_b32_e32 v189, v181
	v_mov_b64_e32 v[190:191], 0x200
	v_mov_b64_e32 v[192:193], 0x1ff
	v_add_u32_e32 v208, s72, v206
	v_add_u32_e32 v209, s73, v206
	v_add_u32_e32 v210, 0, v6
	v_mbcnt_hi_u32_b32 v211, -1, v222
	s_mov_b32 s74, 0
	s_barrier
	v_readfirstlane_b32 s99, v0
	s_nop 3
	s_lshr_b32 s99, s99, 8
	s_cmp_eq_u32 s99, 0
	s_cbranch_scc0 .Lprio_skip_5
	s_setprio 1

; #define PG8_STAGE(bufoff, gbase, voff) do { _Pragma("unroll") for (int _i = 0; _i < 2; ++_i) \
;         __builtin_amdgcn_global_load_lds((const unsigned*)((const char*)(gbase) + (voff)[_i]), (PG8_LAS unsigned*)(lds + (bufoff) + ldsw + _i * 8192), 16, 0, 0); } while (0)
; #define PG8_WAIT_V(n) asm volatile("s_waitcnt vmcnt(" #n ")" ::: "memory")
; #define PG8_BAR __builtin_amdgcn_s_barrier()
; template <class Epi, class Sched, bool ALIGN_EPI = false, bool SP2 = false>
; __device__ __forceinline__ void gemm_phase(PG8_LAS unsigned char* lds, const Gemm g, const Sched& S, const Epi& E) {
;     ...
;     const int aoff = lds_byte(wr * 64 + fr, fq * 8), boff = lds_byte(wc * 32 + fr, fq * 8);
;     ...
;         PG8_WAIT_V(2); PG8_BAR;
;         PG8_STAGE(PG8_SB(1, 0), cB + kstep, voffB); PG8_STAGE(PG8_SA(1, 0), cA + kstep, voffA); PG8_STAGE(PG8_SB(1, 1), cB + hB + kstep, voffB);
;         PG8_WAIT_V(6); PG8_BAR;
.LBB0_1042:
	s_add_u32 s16, s6, 0x5800000
	s_addc_u32 s17, s7, 0
	s_lshl_b32 s18, s20, 5
	s_mov_b64 s[20:21], 0x80
	s_and_b32 s18, s18, 0x60
	s_add_i32 m0, s51, 0x18000
	v_lshl_add_u64 v[8:9], v[8:9], 0, s[20:21]
	s_lshl_b32 s1, s24, 13
	s_lshl_b32 s19, s18, 7
	s_waitcnt vmcnt(2)
	s_barrier
	global_load_lds_dwordx4 v[8:9], off
	v_lshl_add_u64 v[6:7], v[6:7], 0, s[20:21]
	s_add_i32 m0, s51, 0x1a000
	s_add_i32 s60, s51, 0x8000
	s_add_i32 s61, s51, 0xa000
	global_load_lds_dwordx4 v[6:7], off
	v_lshl_add_u64 v[2:3], v[2:3], 0, s[20:21]
	s_mov_b32 m0, s60
	s_add_u32 s36, s42, 0x80080
	global_load_lds_dwordx4 v[2:3], off
	v_lshl_add_u64 v[2:3], v[4:5], 0, s[20:21]
	s_mov_b32 m0, s61
	s_addc_u32 s37, s43, 0
	global_load_lds_dwordx4 v[2:3], off
	s_add_i32 m0, s51, 0x1c000
	v_lshl_add_u64 v[2:3], s[36:37], 0, v[134:135]
	global_load_lds_dwordx4 v[2:3], off
	v_lshl_add_u64 v[2:3], s[36:37], 0, v[130:131]
	s_add_i32 m0, s51, 0x1e000
	s_cmpk_lt_u32 s23, 0x100
	global_load_lds_dwordx4 v[2:3], off
	v_lshrrev_b32_e32 v3, 1, v12
	v_and_b32_e32 v4, 24, v3
	v_and_b32_e32 v2, 15, v12
	v_lshlrev_b32_e32 v3, 1, v4
	v_lshl_or_b32 v1, s24, 6, v2
	v_lshl_or_b32 v2, v2, 6, v3
	v_lshlrev_b32_e32 v3, 2, v12
	v_and_b32_e32 v3, 32, v3
	v_bitop3_b32 v5, v2, s1, v3 bitop3:0xde
	v_bitop3_b32 v165, v2, s19, v3 bitop3:0xde
	v_lshlrev_b32_e32 v2, 2, v4
	v_mov_b32_e32 v3, v135
	v_lshl_add_u64 v[2:3], s[6:7], 0, v[2:3]
	s_mov_b64 s[6:7], 0x1e00000
	v_lshl_add_u64 v[138:139], v[2:3], 0, s[6:7]
	v_lshlrev_b32_e32 v2, 15, v15
	v_and_b32_e32 v2, 0xffff0000, v2
	v_lshl_add_u32 v2, v14, 12, v2
	v_and_b32_e32 v3, 1, v15
	v_lshl_or_b32 v2, v3, 6, v2
	v_lshl_add_u32 v140, v16, 1, v2
	v_lshlrev_b32_e32 v2, 15, v10
	v_and_b32_e32 v2, 0xffff0000, v2
	s_waitcnt vmcnt(6)
	v_lshl_add_u32 v2, v11, 12, v2
	v_and_b32_e32 v3, 1, v10
	s_sext_i32_i16 s67, s22
	s_cselect_b64 s[22:23], -1, 0
	v_lshl_or_b32 v2, v3, 6, v2
	s_add_i32 s63, 0, 0x10000
	s_add_i32 s64, 0, 0x14000
	s_waitcnt lgkmcnt(0)
	s_ashr_i32 s62, s58, 31
	v_or_b32_e32 v167, s18, v4
	v_mov_b32_e32 v141, v135
	v_lshl_add_u32 v142, v13, 1, v2
	v_mov_b32_e32 v143, v135
	v_mov_b64_e32 v[144:145], 0xb00
	v_mov_b64_e32 v[146:147], 0xaff
	v_add_u32_e32 v169, s63, v165
	v_add_u32_e32 v171, s64, v165
	v_add_u32_e32 v173, 0, v5
	v_mbcnt_hi_u32_b32 v175, -1, v222
	v_mov_b32_e32 v177, 0x358637bd
	s_mov_b32 s65, 0xf800000
	v_mov_b32_e32 v179, 0x260
	s_movk_i32 s66, 0x2c00
	s_barrier
	s_mov_b32 s98, -1
	v_readfirstlane_b32 s99, v0
	s_nop 3
	s_lshr_b32 s99, s99, 8
	s_cmp_eq_u32 s99, 0
	s_cbranch_scc0 .Lprio_skip_6
	s_setprio 1

; #define PG8_STAGE(bufoff, gbase, voff) do { _Pragma("unroll") for (int _i = 0; _i < 2; ++_i) \
;         __builtin_amdgcn_global_load_lds((const unsigned*)((const char*)(gbase) + (voff)[_i]), (PG8_LAS unsigned*)(lds + (bufoff) + ldsw + _i * 8192), 16, 0, 0); } while (0)
; #define PG8_WAIT_V(n) asm volatile("s_waitcnt vmcnt(" #n ")" ::: "memory")
; #define PG8_BAR __builtin_amdgcn_s_barrier()
; template <class Epi, class Sched, bool ALIGN_EPI = false, bool SP2 = false>
; __device__ __forceinline__ void gemm_phase(PG8_LAS unsigned char* lds, const Gemm g, const Sched& S, const Epi& E) {
;     ...
;     const int aoff = lds_byte(wr * 64 + fr, fq * 8), boff = lds_byte(wc * 32 + fr, fq * 8);
;     ...
;         PG8_WAIT_V(2); PG8_BAR;
;         PG8_STAGE(PG8_SB(1, 0), cB + kstep, voffB); PG8_STAGE(PG8_SA(1, 0), cA + kstep, voffA); PG8_STAGE(PG8_SB(1, 1), cB + hB + kstep, voffB);
;         PG8_WAIT_V(6); PG8_BAR;
.LBB0_1113:
	s_add_u32 s12, s6, 0x15800000
	s_addc_u32 s13, s7, 0
	s_add_u32 s14, s6, 0x2000000
	s_mov_b64 s[16:17], 0x80
	s_addc_u32 s15, s7, 0
	s_and_b32 s51, s4, 3
	s_add_i32 m0, s46, 0x18000
	v_lshl_add_u64 v[8:9], v[8:9], 0, s[16:17]
	s_lshl_b32 s4, s5, 13
	s_lshl_b32 s18, s51, 12
	s_waitcnt vmcnt(2)
	s_barrier
	global_load_lds_dwordx4 v[8:9], off
	v_lshl_add_u64 v[4:5], v[4:5], 0, s[16:17]
	s_add_i32 m0, s46, 0x1a000
	s_add_i32 s52, s46, 0x8000
	s_add_i32 s53, s46, 0xa000
	global_load_lds_dwordx4 v[4:5], off
	v_lshl_add_u64 v[2:3], v[2:3], 0, s[16:17]
	s_mov_b32 m0, s52
	s_add_u32 s6, s36, 0x160080
	global_load_lds_dwordx4 v[2:3], off
	v_lshl_add_u64 v[2:3], v[6:7], 0, s[16:17]
	s_mov_b32 m0, s53
	s_addc_u32 s7, s37, 0
	global_load_lds_dwordx4 v[2:3], off
	s_add_i32 m0, s46, 0x1c000
	v_lshl_add_u64 v[2:3], s[6:7], 0, v[156:157]
	global_load_lds_dwordx4 v[2:3], off
	v_lshl_add_u64 v[2:3], s[6:7], 0, v[160:161]
	s_add_i32 m0, s46, 0x1e000
	s_mov_b64 s[6:7], 0x160080
	global_load_lds_dwordx4 v[2:3], off
	v_bfe_u32 v3, v10, 4, 2
	v_and_b32_e32 v2, 15, v10
	v_lshlrev_b32_e32 v5, 4, v3
	v_lshl_or_b32 v1, s5, 6, v2
	v_lshl_or_b32 v2, v2, 6, v5
	v_lshlrev_b32_e32 v5, 2, v10
	v_and_b32_e32 v5, 32, v5
	v_lshlrev_b32_e32 v4, 3, v3
	v_bitop3_b32 v6, v2, s4, v5 bitop3:0xde
	v_bitop3_b32 v188, v2, s18, v5 bitop3:0xde
	v_cmp_eq_u32_e64 s[4:5], 0, v3
	v_lshrrev_b32_e32 v3, 1, v11
	v_mul_lo_u32 v2, v12, s9
	v_mad_u64_u32 v[2:3], s[38:39], v3, s22, v[2:3]
	v_or_b32_e32 v2, v2, v13
	v_add_lshl_u32 v2, v2, v14, 1
	v_mov_b32_e32 v3, v157
	v_lshl_add_u64 v[162:163], v[2:3], 0, s[6:7]
	v_lshrrev_b32_e32 v3, 1, v15
	v_mul_lo_u32 v2, v16, s9
	s_cmpk_lt_u32 s8, 0x100
	v_mad_u64_u32 v[2:3], s[8:9], v3, s22, v[2:3]
	s_waitcnt vmcnt(6)
	v_or_b32_e32 v2, v2, v17
	s_cselect_b64 s[20:21], -1, 0
	v_add_lshl_u32 v2, v2, v18, 1
	v_mov_b32_e32 v3, v157
	s_add_i32 s55, 0, 0x10000
	s_add_i32 s56, 0, 0x14000
	v_lshl_or_b32 v189, s51, 5, v4
	s_waitcnt lgkmcnt(0)
	s_ashr_i32 s54, s50, 31
	v_lshl_add_u64 v[164:165], v[2:3], 0, s[6:7]
	v_mov_b64_e32 v[166:167], 0x200
	v_mov_b64_e32 v[168:169], 0x1ff
	v_add_u32_e32 v190, s55, v188
	v_add_u32_e32 v191, s56, v188
	v_add_u32_e32 v192, 0, v6
	v_mbcnt_hi_u32_b32 v193, -1, v222
	s_mov_b32 s57, 0
	s_barrier
	v_readfirstlane_b32 s99, v0
	s_nop 3
	s_lshr_b32 s99, s99, 8
	s_cmp_eq_u32 s99, 0
	s_cbranch_scc0 .Lprio_skip_7
	s_setprio 1
